# P8 split-K sample-row units handed out by atomic ticket (first finishers take them)
# speedup vs baseline: 1.0059x; 1.0059x over previous
.LBB0_1650:
	v_cmp_eq_u32_e64 s[100:101], 0, v185
	s_and_saveexec_b64 s[98:99], s[100:101]
	s_cbranch_execz .Lsk8_a
	v_readlane_b32 s100, v251, 6
	v_readlane_b32 s101, v251, 7
	v_mov_b32_e32 v238, 0
	v_mov_b32_e32 v239, 1
	s_nop 3
	global_atomic_add v239, v238, v239, s[100:101] offset:512 sc0
	s_waitcnt vmcnt(0)
	v_mov_b32_e32 v238, 0x26a00
	ds_write_b32 v238, v239
.Lsk8_a:
	s_or_b64 exec, exec, s[98:99]
	s_waitcnt lgkmcnt(0)
	s_barrier
	v_mov_b32_e32 v238, 0x26a00
	ds_read_b32 v238, v238
	s_waitcnt lgkmcnt(0)
	v_readfirstlane_b32 s98, v238
	s_nop 3
	s_and_b32 s100, s98, 1
	s_bfe_u32 s101, s98, 0x20001
	v_mov_b32_e32 v16, v185
	s_movk_i32 s0, 0x800
	v_readfirstlane_b32 s24, v16
	s_cmp_gt_i32 s98, 63
	s_cbranch_scc1 .LBB0_1664
	v_lshlrev_b32_e32 v2, 4, v16
	v_add_u32_e32 v0, 0x2000, v2
	v_ashrrev_i32_e32 v1, 31, v0
	v_lshrrev_b32_e32 v1, 22, v1
	v_add_u32_e32 v1, v0, v1
	v_ashrrev_i32_e32 v1, 10, v1
	v_mul_i32_i24_e32 v3, 0x400, v1
	v_sub_u32_e32 v0, v0, v3
	v_lshrrev_b32_e32 v3, 4, v0
	v_bitop3_b32 v3, v3, v0, 32 bitop3:0x6c
	v_ashrrev_i32_e32 v0, 31, v3
	v_lshrrev_b32_e32 v0, 26, v0
	v_add_u32_e32 v4, v3, v0
	v_lshlrev_b32_e32 v5, 3, v1
	v_ashrrev_i32_e32 v0, 6, v4
	v_and_b32_e32 v5, 0x7ffffff0, v5
	v_add_u32_e32 v5, v0, v5
	v_lshlrev_b32_e32 v0, 5, v1
	v_and_b32_e32 v0, 32, v0
	v_mad_u64_u32 v[0:1], s[6:7], v5, s0, v[0:1]
	v_and_b32_e32 v1, 0xc0, v4
	v_sub_u32_e32 v1, v3, v1
	v_mov_b32_e32 v4, 1
	v_ashrrev_i16_sdwa v1, v4, sext(v1) dst_sel:DWORD dst_unused:UNUSED_PAD src0_sel:DWORD src1_sel:BYTE_0
	v_bfe_i32 v1, v1, 0, 16
	v_add_lshl_u32 v0, v0, v1, 1
	v_bfe_i32 v1, v16, 27, 1
	v_lshrrev_b32_e32 v1, 22, v1
	v_add_u32_e32 v1, v2, v1
	v_and_b32_e32 v1, 0xfffffc00, v1
	v_sub_u32_e32 v1, v2, v1
	v_lshrrev_b32_e32 v2, 4, v1
	v_ashrrev_i32_e32 v3, 31, v16
	v_bitop3_b32 v1, v2, v1, 32 bitop3:0x6c
	v_lshrrev_b32_e32 v3, 26, v3
	v_ashrrev_i32_e32 v2, 31, v1
	v_add_u32_e32 v3, v16, v3
	v_lshrrev_b32_e32 v2, 26, v2
	v_ashrrev_i32_e32 v3, 6, v3
	v_add_u32_e32 v5, v1, v2
	v_lshlrev_b32_e32 v6, 3, v3
	v_ashrrev_i32_e32 v2, 6, v5
	v_and_b32_e32 v6, 0x7ffffff0, v6
	v_add_u32_e32 v6, v2, v6
	v_lshlrev_b32_e32 v2, 5, v3
	v_and_b32_e32 v2, 32, v2
	s_add_u32 s25, s54, 0x12e94000
	v_mad_u64_u32 v[2:3], s[6:7], v6, s0, v[2:3]
	s_addc_u32 s26, s55, 0
	s_lshl_b32 s6, s98, 5
	s_ashr_i32 s1, s0, 31
	s_and_b32 s8, s6, 0xffffff00
	s_lshl_b64 s[2:3], s[0:1], 8
	s_lshl_b64 s[4:5], s[0:1], 9
	s_lshr_b64 s[0:1], s[0:1], 23
	s_ashr_i32 s9, s8, 31
	s_ashr_i32 s10, s24, 6
	s_mul_i32 s1, s0, s100
	s_lshl_b64 s[6:7], s[8:9], 1
	s_mul_i32 s0, s0, s101
	s_mul_hi_u32 s9, s4, s101
	s_ashr_i32 s11, s24, 8
	s_lshl_b32 s14, s10, 10
	s_add_i32 s9, s9, s0
	s_mul_i32 s0, s4, s101
	v_readlane_b32 s16, v251, 41
	v_and_b32_e32 v3, 0xc0, v5
	v_readlane_b32 s17, v251, 42
	s_add_u32 s0, s16, s0
	v_sub_u32_e32 v1, v1, v3
	s_addc_u32 s9, s17, s9
	v_ashrrev_i16_sdwa v1, v4, sext(v1) dst_sel:DWORD dst_unused:UNUSED_PAD src0_sel:DWORD src1_sel:BYTE_0
	s_add_u32 s20, s0, s6
	v_bfe_i32 v1, v1, 0, 16
	s_addc_u32 s21, s9, s7
	s_add_i32 s9, s14, 0
	v_add_lshl_u32 v2, v2, v1, 1
	s_add_i32 m0, s9, 0x10000
	s_mul_i32 s12, s4, s100
	global_load_lds_dwordx4 v2, s[20:21]
	s_add_i32 m0, s9, 0x12000
	s_add_u32 s0, s25, s12
	s_addc_u32 s1, s26, s1
	s_add_u32 s22, s0, s6
	global_load_lds_dwordx4 v0, s[20:21]
	s_addc_u32 s23, s1, s7
	s_mov_b32 m0, s9
	s_add_i32 s27, s9, 0x2000
	global_load_lds_dwordx4 v2, s[22:23]
	s_mov_b32 m0, s27
	s_add_u32 s0, s20, s2
	global_load_lds_dwordx4 v0, s[22:23]
	s_addc_u32 s1, s21, s3
	s_add_i32 m0, s9, 0x14000
	v_mov_b32_e32 v3, 0
	global_load_lds_dwordx4 v2, s[0:1]
	s_add_i32 m0, s9, 0x16000
	s_add_u32 s6, s22, s2
	s_addc_u32 s7, s23, s3
	s_add_i32 s28, s9, 0x4000
	global_load_lds_dwordx4 v0, s[0:1]
	s_mov_b32 m0, s28
	s_add_i32 s29, s9, 0x6000
	global_load_lds_dwordx4 v2, s[6:7]
	s_mov_b32 m0, s29
	s_mov_b64 s[66:67], s[54:55]
	global_load_lds_dwordx4 v0, s[6:7]
	v_mov_b32_e32 v1, v3
	s_mov_b64 s[64:65], s[52:53]
	s_mov_b64 s[62:63], s[50:51]
	v_lshl_add_u64 v[14:15], s[20:21], 0, v[2:3]
	v_lshl_add_u64 v[12:13], s[20:21], 0, v[0:1]
	v_lshl_add_u64 v[10:11], s[22:23], 0, v[2:3]
	v_lshl_add_u64 v[8:9], s[22:23], 0, v[0:1]
	v_lshl_add_u64 v[6:7], s[0:1], 0, v[2:3]
	s_cmp_lg_u32 s11, 1
	v_lshl_add_u64 v[4:5], s[0:1], 0, v[0:1]
	s_cbranch_scc1 .LBB0_1653
	s_barrier
.LBB0_1653:
	s_mov_b64 s[6:7], 0x80
	s_add_i32 m0, s9, 0x18000
	v_lshl_add_u64 v[14:15], v[14:15], 0, s[6:7]
	s_waitcnt vmcnt(4)
	s_barrier
	global_load_lds_dwordx4 v[14:15], off
	v_lshl_add_u64 v[12:13], v[12:13], 0, s[6:7]
	s_add_i32 m0, s9, 0x1a000
	s_add_i32 s30, s9, 0x8000
	global_load_lds_dwordx4 v[12:13], off
	v_lshl_add_u64 v[10:11], v[10:11], 0, s[6:7]
	s_mov_b32 m0, s30
	s_add_i32 s31, s9, 0xa000
	global_load_lds_dwordx4 v[10:11], off
	v_lshl_add_u64 v[8:9], v[8:9], 0, s[6:7]
	s_mov_b32 m0, s31
	v_lshl_add_u64 v[6:7], v[6:7], 0, s[6:7]
	global_load_lds_dwordx4 v[8:9], off
	s_add_i32 m0, s9, 0x1c000
	v_lshl_add_u64 v[4:5], v[4:5], 0, s[6:7]
	global_load_lds_dwordx4 v[6:7], off
	s_add_i32 m0, s9, 0x1e000
	s_lshl_b32 s0, s11, 13
	global_load_lds_dwordx4 v[4:5], off
	v_bfe_u32 v5, v16, 4, 2
	v_and_b32_e32 v4, 15, v16
	v_lshlrev_b32_e32 v6, 4, v5
	v_lshl_or_b32 v8, s11, 6, v4
	v_lshl_or_b32 v4, v4, 6, v6
	v_lshlrev_b32_e32 v6, 2, v16
	v_and_b32_e32 v6, 32, v6
	v_bitop3_b32 v7, v4, s0, v6 bitop3:0xde
	s_lshl_b32 s0, s10, 5
	s_and_b32 s0, s0, 0x60
	s_lshl_b32 s1, s0, 7
	v_bitop3_b32 v4, v4, s1, v6 bitop3:0xde
	s_waitcnt vmcnt(6)
	s_add_i32 s43, 0, 0x10000
	s_add_i32 s45, 0, 0x14000
	s_add_i32 s47, 0, 0x18000
	s_add_i32 s49, 0, 0x1c000
	v_lshl_or_b32 v12, v5, 2, s0
	s_add_i32 s0, s94, s98
	v_add_u32_e32 v13, s43, v4
	v_add_u32_e32 v15, s45, v4
	s_add_i32 s43, s43, s14
	s_add_i32 s45, s45, s14
	v_add_u32_e32 v16, s47, v4
	v_add_u32_e32 v17, s49, v4
	s_add_i32 s47, s47, s14
	s_add_i32 s49, s49, s14
	v_or_b32_e32 v9, 16, v8
	v_or_b32_e32 v10, 32, v8
	v_or_b32_e32 v11, 48, v8
	s_lshl_b32 s33, s0, 5
	s_lshl_b32 s40, s94, 5
	v_add_u32_e32 v14, 0, v7
	s_add_i32 s41, s9, 0xc000
	s_add_i32 s42, s9, 0xe000
	s_mov_b64 s[10:11], 0x100
	s_mov_b64 s[12:13], 0x180
	s_add_i32 s44, s43, 0x2000
	s_add_i32 s46, s45, 0x2000
	s_add_i32 s48, s47, 0x2000
	s_add_i32 s50, s49, 0x2000
	s_mov_b32 s51, s98
	s_mov_b32 s54, s101
	s_mov_b32 s55, s100
	s_barrier
	s_branch .LBB0_1655
